# attention k-loop: softmax row sums via v_pk_add_f32 (second group's exps in place), 11 fewer VALU per step; f32 accumulation kept
# baseline (speedup 1.0000x reference)
; DEV void attn_item(const Params& p, int item, char* smem) {
;     ...
;       lrun[jt] += (((pv[0] + pv[1]) + (pv[2] + pv[3])) + ((pv[4] + pv[5]) + (pv[6] + pv[7]))) +
;                   (((pv[8] + pv[9]) + (pv[10] + pv[11])) + ((pv[12] + pv[13]) + (pv[14] + pv[15])));
;     ...
;     if (kt + 1 < ntile) {
;       bf16_t* Kn = Ks + ((kt + 1) & 1) * (32 * ASTR);
;       bf16_t* Vn = Vs + ((kt + 1) & 1) * (64 * VSTR);
;       *(u32x4*)(Kn + k0row * ASTR + k0cc * 8) = rk0;
;       if (has_k1) *(u32x4*)(Kn + k1row * ASTR + k1cc * 8) = rk1;
;       *(uint2*)(Vn + vrow * VSTR + vcc * 8) = make_uint2(rv0[0], rv0[1]);
;       *(uint2*)(Vn + vrow * VSTR + vcc * 8 + 4) = make_uint2(rv0[2], rv0[3]);
;       __syncthreads();
;       if (kt + 2 < ntile) {
;         rk0 = *(const u32x4*)(Kb + (size_t)((kt + 2) * 32 + k0row) * 96 + k0cc * 8);
;         rk1 = *(const u32x4*)(Kb + (size_t)((kt + 2) * 32 + k1row) * 96 + k1cc * 8);
;         rv0 = *(const u32x4*)(Vb + (size_t)vrow * 8448 + (kt + 2) * 32 + vcc * 8);
;       }
.LBB0_752:
	s_or_b64 exec, exec, s[8:9]
	v_pk_add_f32 v[4:5], v[80:81], v[82:83]
	v_pk_add_f32 v[6:7], v[84:85], v[86:87]
	v_pk_add_f32 v[8:9], v[88:89], v[90:91]
	v_pk_add_f32 v[10:11], v[92:93], v[94:95]
	v_pk_add_f32 v[12:13], v[100:101], v[102:103]
	v_pk_add_f32 v[2:3], v[104:105], v[106:107]
	v_pk_add_f32 v[4:5], v[4:5], v[6:7]
	v_pk_add_f32 v[8:9], v[8:9], v[10:11]
	v_pk_add_f32 v[12:13], v[12:13], v[108:109]
	v_add_f32_e32 v0, v0, v193
	v_add_f32_e32 v6, v194, v239
	v_add_f32_e32 v7, v240, v110
	v_pk_add_f32 v[4:5], v[4:5], v[8:9]
	v_pk_add_f32 v[2:3], v[2:3], v[12:13]
	v_add_f32_e32 v0, v0, v6
	s_mul_i32 s8, s14, 0x1600
	v_add_f32_e32 v4, v4, v5
	v_add_f32_e32 v2, v2, v3
	v_add_f32_e32 v0, v0, v7
	v_add_f32_e32 v184, v184, v4
	v_add_f32_e32 v0, v0, v2
	v_add_f32_e32 v14, v14, v0
	v_add_u32_e32 v0, s8, v217
	ds_write2_b64 v0, v[160:161], v[162:163] offset1:1
	s_waitcnt lgkmcnt(0)
	s_barrier
	global_load_dwordx4 v[168:171], v[182:183], off
	global_load_dwordx4 v[164:167], v[180:181], off
	global_load_dwordx4 v[160:163], v[178:179], off
	s_mov_b64 s[8:9], 0x1800
	v_lshl_add_u64 v[178:179], v[178:179], 0, 64
	v_lshl_add_u64 v[180:181], v[180:181], 0, s[8:9]
	v_lshl_add_u64 v[182:183], v[182:183], 0, s[8:9]
	s_cmp_eq_u32 s13, s12
	s_cbranch_scc1 .LBB0_759

; DEV unsigned pack2(float a, float b) { f32x2 v = {a, b}; return __builtin_bit_cast(unsigned, __builtin_convertvector(v, bf2_t)); }
; DEV f32x16 mfma32(bf16x8 a, bf16x8 b, f32x16 c) { return __builtin_amdgcn_mfma_f32_32x32x16_bf16(a, b, c, 0, 0, 0); }
; DEV void attn_item(const Params& p, int item, char* smem) {
;     ...
;       for (int r = 0; r < 16; r++) pv[r] = __builtin_amdgcn_exp2f(s[jt][r] - mcur);
;       lrun[jt] += (((pv[0] + pv[1]) + (pv[2] + pv[3])) + ((pv[4] + pv[5]) + (pv[6] + pv[7]))) +
;                   (((pv[8] + pv[9]) + (pv[10] + pv[11])) + ((pv[12] + pv[13]) + (pv[14] + pv[15])));
;       bf16x8 pf[2];
; #pragma unroll
;       for (int ss = 0; ss < 2; ss++) {
;         uint4 u; u.x = pack2(pv[8 * ss + 0], pv[8 * ss + 1]); u.y = pack2(pv[8 * ss + 2], pv[8 * ss + 3]);
;         u.z = pack2(pv[8 * ss + 4], pv[8 * ss + 5]); u.w = pack2(pv[8 * ss + 6], pv[8 * ss + 7]);
;         pf[ss] = __builtin_bit_cast(bf16x8, u);
;       }
; #pragma unroll
;       for (int dt = 0; dt < 2; dt++)
; #pragma unroll
;         for (int ss = 0; ss < 2; ss++) {
;           uint2 lo = *(const uint2*)(Vc + (dt * 32 + c31) * VSTR + 16 * ss + 4 * hf);
;           uint2 hi = *(const uint2*)(Vc + (dt * 32 + c31) * VSTR + 16 * ss + 8 + 4 * hf);
;           uint4 u; u.x = lo.x; u.y = lo.y; u.z = hi.x; u.w = hi.y;
;           o[dt][jt] = mfma32(__builtin_bit_cast(bf16x8, u), pf[ss], o[dt][jt]);
;         }
;     }
;     if (kt + 1 < ntile) {
;       bf16_t* Kn = Ks + ((kt + 1) & 1) * (32 * ASTR);
;       bf16_t* Vn = Vs + ((kt + 1) & 1) * (64 * VSTR);
;       *(u32x4*)(Kn + k0row * ASTR + k0cc * 8) = rk0;
;       if (has_k1) *(u32x4*)(Kn + k1row * ASTR + k1cc * 8) = rk1;
;       *(uint2*)(Vn + vrow * VSTR + vcc * 8) = make_uint2(rv0[0], rv0[1]);
;       *(uint2*)(Vn + vrow * VSTR + vcc * 8 + 4) = make_uint2(rv0[2], rv0[3]);
.LBB0_757:
	v_exp_f32_e32 v80, v80
	v_exp_f32_e32 v81, v81
	v_exp_f32_e32 v82, v82
	v_exp_f32_e32 v83, v83
	v_exp_f32_e32 v84, v84
	v_exp_f32_e32 v85, v85
	v_exp_f32_e32 v86, v86
	v_exp_f32_e32 v87, v87
	v_exp_f32_e32 v88, v88
	v_exp_f32_e32 v89, v89
	v_exp_f32_e32 v90, v90
	v_cvt_pk_bf16_f32 v242, v80, v81
	v_cvt_pk_bf16_f32 v243, v82, v83
	v_cvt_pk_bf16_f32 v244, v84, v85
	v_cvt_pk_bf16_f32 v245, v86, v87
	v_exp_f32_e32 v91, v91
	v_exp_f32_e32 v92, v92
	v_mfma_f32_32x32x16_bf16 v[64:79], v[2:5], v[242:245], v[64:79]
	v_exp_f32_e32 v93, v93
	v_exp_f32_e32 v94, v94
	v_exp_f32_e32 v95, v95
	v_mfma_f32_32x32x16_bf16 v[48:63], v[10:13], v[242:245], v[48:63]
	v_cvt_pk_bf16_f32 v246, v88, v89
	v_cvt_pk_bf16_f32 v247, v90, v91
	v_cvt_pk_bf16_f32 v248, v92, v93
	v_cvt_pk_bf16_f32 v249, v94, v95
	s_add_i32 s12, s12, 1
	s_and_b32 s14, s12, 1
	s_mul_i32 s15, s14, 0x1a00
	v_mfma_f32_32x32x16_bf16 v[64:79], v[6:9], v[246:249], v[64:79]
	v_add_u32_e32 v4, s15, v214
	s_waitcnt vmcnt(0)
	ds_write_b128 v4, v[168:171]
	v_mfma_f32_32x32x16_bf16 v[48:63], v[96:99], v[246:249], v[48:63]
	s_and_saveexec_b64 s[8:9], s[38:39]
	s_cbranch_execz .LBB0_752
	v_add_u32_e32 v4, s15, v251
	ds_write_b128 v4, v[164:167]
	s_branch .LBB0_752
